# attention softmax: row-sum accumulators initialised by the first add instead of v_mov (6 fewer VALU per wave-tile)
# speedup vs baseline: 1.0047x; 1.0047x over previous
.LBB0_711:
	s_cmp_ge_u32 s55, s78
	s_cbranch_scc1 .LBB0_717
	s_and_b32 s55, s50, 0x4000
	v_add_u32_e32 v16, s55, v198
	v_add_u32_e32 v216, v199, v16
	ds_read_b128 v[220:223], v216
	ds_read_b128 v[224:227], v216 offset:8192
	ds_read_b128 v[228:231], v205
	v_xad_u32 v217, v199, 32, v16
	ds_read_b128 v[232:235], v217
	ds_read_b128 v[236:239], v217 offset:8192
	ds_read_b128 v[240:243], v205 offset:32
	v_xad_u32 v216, v199, 64, v16
	ds_read_b128 v[244:247], v216
	ds_read_b128 v[248:251], v216 offset:8192
	ds_read_b128 v[200:203], v205 offset:64
	v_xad_u32 v217, v199, s79, v16
	ds_read_b128 v[208:211], v217
	ds_read_b128 v[212:215], v217 offset:8192
	s_waitcnt lgkmcnt(8)
	v_mfma_f32_32x32x16_bf16 v[162:177], v[220:223], v[228:231], 0
	v_mfma_f32_32x32x16_bf16 v[146:161], v[224:227], v[228:231], 0
	ds_read_b128 v[220:223], v205 offset:96
	s_waitcnt lgkmcnt(6)
	v_mfma_f32_32x32x16_bf16 v[162:177], v[232:235], v[240:243], v[162:177]
	v_mfma_f32_32x32x16_bf16 v[146:161], v[236:239], v[240:243], v[146:161]
	s_waitcnt lgkmcnt(3)
	v_mfma_f32_32x32x16_bf16 v[162:177], v[244:247], v[200:203], v[162:177]
	v_mfma_f32_32x32x16_bf16 v[146:161], v[248:251], v[200:203], v[146:161]
	s_waitcnt lgkmcnt(0)
	v_mfma_f32_32x32x16_bf16 v[162:177], v[208:211], v[220:223], v[162:177]
	v_mfma_f32_32x32x16_bf16 v[146:161], v[212:215], v[220:223], v[146:161]
	v_xad_u32 v254, v199, s80, v16
	ds_read_b128 v[200:203], v254
	ds_read_b128 v[208:211], v254 offset:8192
	ds_read_b128 v[212:215], v205 offset:128
	s_nop 7
	v_fma_f32 v216, v162, s97, -v207
	v_fma_f32 v217, v163, s97, -v207
	v_fma_f32 v252, v164, s97, -v207
	v_fma_f32 v253, v165, s97, -v207
	v_exp_f32_e32 v216, v216
	v_exp_f32_e32 v217, v217
	v_exp_f32_e32 v252, v252
	v_exp_f32_e32 v253, v253
	v_cvt_pk_bf16_f32 v178, v216, v217
	v_cvt_pk_bf16_f32 v179, v252, v253
	v_add_f32_e32 v17, v252, v216
	v_add_f32_e32 v219, v253, v217
	s_waitcnt lgkmcnt(0)
	v_mfma_f32_32x32x16_bf16 v[220:235], v[200:203], v[212:215], 0
	v_mfma_f32_32x32x16_bf16 v[236:251], v[208:211], v[212:215], 0
	v_xad_u32 v204, v199, s81, v16
	ds_read_b128 v[200:203], v204
	ds_read_b128 v[208:211], v204 offset:8192
	ds_read_b128 v[212:215], v205 offset:160
	v_fma_f32 v216, v166, s97, -v207
	v_fma_f32 v217, v167, s97, -v207
	v_fma_f32 v252, v168, s97, -v207
	v_fma_f32 v253, v169, s97, -v207
	v_exp_f32_e32 v216, v216
	v_exp_f32_e32 v217, v217
	v_exp_f32_e32 v252, v252
	v_exp_f32_e32 v253, v253
	v_add_f32_e32 v17, v216, v17
	v_add_f32_e32 v219, v217, v219
	v_cvt_pk_bf16_f32 v180, v216, v217
	v_cvt_pk_bf16_f32 v181, v252, v253
	v_add_f32_e32 v17, v252, v17
	v_add_f32_e32 v219, v253, v219
	s_waitcnt lgkmcnt(0)
	v_mfma_f32_32x32x16_bf16 v[220:235], v[200:203], v[212:215], v[220:235]
	v_mfma_f32_32x32x16_bf16 v[236:251], v[208:211], v[212:215], v[236:251]
	v_xad_u32 v254, v199, s82, v16
	ds_read_b128 v[200:203], v254
	ds_read_b128 v[208:211], v254 offset:8192
	ds_read_b128 v[212:215], v205 offset:192
	v_fma_f32 v216, v170, s97, -v207
	v_fma_f32 v217, v171, s97, -v207
	v_fma_f32 v252, v172, s97, -v207
	v_fma_f32 v253, v173, s97, -v207
	v_exp_f32_e32 v216, v216
	v_exp_f32_e32 v217, v217
	v_exp_f32_e32 v252, v252
	v_exp_f32_e32 v253, v253
	v_add_f32_e32 v17, v216, v17
	v_add_f32_e32 v219, v217, v219
	v_cvt_pk_bf16_f32 v12, v216, v217
	v_cvt_pk_bf16_f32 v13, v252, v253
	v_add_f32_e32 v17, v252, v17
	v_add_f32_e32 v219, v253, v219
	s_waitcnt lgkmcnt(0)
	v_mfma_f32_32x32x16_bf16 v[220:235], v[200:203], v[212:215], v[220:235]
	v_mfma_f32_32x32x16_bf16 v[236:251], v[208:211], v[212:215], v[236:251]
	v_xad_u32 v204, v199, s83, v16
	ds_read_b128 v[200:203], v204
	ds_read_b128 v[208:211], v204 offset:8192
	ds_read_b128 v[212:215], v205 offset:224
	v_fma_f32 v216, v174, s97, -v207
	v_fma_f32 v217, v175, s97, -v207
	v_fma_f32 v252, v176, s97, -v207
	v_fma_f32 v253, v177, s97, -v207
	v_exp_f32_e32 v216, v216
	v_exp_f32_e32 v217, v217
	v_exp_f32_e32 v252, v252
	v_exp_f32_e32 v253, v253
	v_add_f32_e32 v17, v216, v17
	v_add_f32_e32 v219, v217, v219
	v_cvt_pk_bf16_f32 v14, v216, v217
	v_cvt_pk_bf16_f32 v15, v252, v253
	v_add_f32_e32 v17, v252, v17
	v_add_f32_e32 v219, v253, v219
	s_waitcnt lgkmcnt(0)
	v_mfma_f32_32x32x16_bf16 v[220:235], v[200:203], v[212:215], v[220:235]
	v_mfma_f32_32x32x16_bf16 v[236:251], v[208:211], v[212:215], v[236:251]
	v_add_f32_e32 v17, v17, v219
	v_cmp_lt_f32_e32 vcc, 0x43800000, v17
	s_cmp_lg_u64 vcc, 0
	s_cbranch_scc0 .Lat_ok0a
	v_max3_f32 v17, v162, v163, v164
	v_max3_f32 v17, v17, v165, v166
	v_max3_f32 v17, v17, v167, v168
	v_max3_f32 v17, v17, v169, v170
	v_max3_f32 v17, v17, v171, v172
	v_max3_f32 v17, v17, v173, v174
	v_max3_f32 v17, v17, v175, v176
	v_max_f32_e32 v17, v17, v177
	v_mov_b32_e32 v219, v17
	s_nop 1
	v_permlane32_swap_b32_e32 v17, v219
	v_max_f32_e32 v17, v17, v219
	v_mul_f32_e32 v17, s97, v17
	v_max_f32_e32 v219, v207, v17
	v_sub_f32_e32 v216, v207, v219
	v_exp_f32_e32 v216, v216
	v_mov_b32_e32 v207, v219
	s_nop 0
	v_pk_mul_f32 v[144:145], v[144:145], v[216:217] op_sel_hi:[1,0]
	v_pk_mul_f32 v[142:143], v[142:143], v[216:217] op_sel_hi:[1,0]
	v_pk_mul_f32 v[140:141], v[140:141], v[216:217] op_sel_hi:[1,0]
	v_pk_mul_f32 v[138:139], v[138:139], v[216:217] op_sel_hi:[1,0]
	v_pk_mul_f32 v[136:137], v[136:137], v[216:217] op_sel_hi:[1,0]
	v_pk_mul_f32 v[134:135], v[134:135], v[216:217] op_sel_hi:[1,0]
	v_pk_mul_f32 v[132:133], v[132:133], v[216:217] op_sel_hi:[1,0]
	v_pk_mul_f32 v[130:131], v[130:131], v[216:217] op_sel_hi:[1,0]
	v_pk_mul_f32 v[112:113], v[112:113], v[216:217] op_sel_hi:[1,0]
	v_pk_mul_f32 v[110:111], v[110:111], v[216:217] op_sel_hi:[1,0]
	v_pk_mul_f32 v[108:109], v[108:109], v[216:217] op_sel_hi:[1,0]
	v_pk_mul_f32 v[106:107], v[106:107], v[216:217] op_sel_hi:[1,0]
	v_pk_mul_f32 v[104:105], v[104:105], v[216:217] op_sel_hi:[1,0]
	v_pk_mul_f32 v[102:103], v[102:103], v[216:217] op_sel_hi:[1,0]
	v_pk_mul_f32 v[100:101], v[100:101], v[216:217] op_sel_hi:[1,0]
	v_pk_mul_f32 v[98:99], v[98:99], v[216:217] op_sel_hi:[1,0]
	v_pk_mul_f32 v[80:81], v[80:81], v[216:217] op_sel_hi:[1,0]
	v_pk_mul_f32 v[78:79], v[78:79], v[216:217] op_sel_hi:[1,0]
	v_pk_mul_f32 v[76:77], v[76:77], v[216:217] op_sel_hi:[1,0]
	v_pk_mul_f32 v[74:75], v[74:75], v[216:217] op_sel_hi:[1,0]
	v_pk_mul_f32 v[72:73], v[72:73], v[216:217] op_sel_hi:[1,0]
	v_pk_mul_f32 v[70:71], v[70:71], v[216:217] op_sel_hi:[1,0]
	v_pk_mul_f32 v[68:69], v[68:69], v[216:217] op_sel_hi:[1,0]
	v_pk_mul_f32 v[66:67], v[66:67], v[216:217] op_sel_hi:[1,0]
	v_pk_mul_f32 v[48:49], v[48:49], v[216:217] op_sel_hi:[1,0]
	v_pk_mul_f32 v[46:47], v[46:47], v[216:217] op_sel_hi:[1,0]
	v_pk_mul_f32 v[44:45], v[44:45], v[216:217] op_sel_hi:[1,0]
	v_pk_mul_f32 v[42:43], v[42:43], v[216:217] op_sel_hi:[1,0]
	v_pk_mul_f32 v[40:41], v[40:41], v[216:217] op_sel_hi:[1,0]
	v_pk_mul_f32 v[38:39], v[38:39], v[216:217] op_sel_hi:[1,0]
	v_pk_mul_f32 v[36:37], v[36:37], v[216:217] op_sel_hi:[1,0]
	v_pk_mul_f32 v[34:35], v[34:35], v[216:217] op_sel_hi:[1,0]
	v_mul_f32_e32 v186, v186, v216
	v_fma_f32 v216, v162, s97, -v207
	v_fma_f32 v217, v163, s97, -v207
	v_fma_f32 v252, v164, s97, -v207
	v_fma_f32 v253, v165, s97, -v207
	v_exp_f32_e32 v216, v216
	v_exp_f32_e32 v217, v217
	v_exp_f32_e32 v252, v252
	v_exp_f32_e32 v253, v253
	v_cvt_pk_bf16_f32 v178, v216, v217
	v_cvt_pk_bf16_f32 v179, v252, v253
	v_add_f32_e32 v17, v252, v216
	v_add_f32_e32 v219, v253, v217
	v_fma_f32 v216, v166, s97, -v207
	v_fma_f32 v217, v167, s97, -v207
	v_fma_f32 v252, v168, s97, -v207
	v_fma_f32 v253, v169, s97, -v207
	v_exp_f32_e32 v216, v216
	v_exp_f32_e32 v217, v217
	v_exp_f32_e32 v252, v252
	v_exp_f32_e32 v253, v253
	v_add_f32_e32 v17, v216, v17
	v_add_f32_e32 v219, v217, v219
	v_cvt_pk_bf16_f32 v180, v216, v217
	v_cvt_pk_bf16_f32 v181, v252, v253
	v_add_f32_e32 v17, v252, v17
	v_add_f32_e32 v219, v253, v219
	v_fma_f32 v216, v170, s97, -v207
	v_fma_f32 v217, v171, s97, -v207
	v_fma_f32 v252, v172, s97, -v207
	v_fma_f32 v253, v173, s97, -v207
	v_exp_f32_e32 v216, v216
	v_exp_f32_e32 v217, v217
	v_exp_f32_e32 v252, v252
	v_exp_f32_e32 v253, v253
	v_add_f32_e32 v17, v216, v17
	v_add_f32_e32 v219, v217, v219
	v_cvt_pk_bf16_f32 v12, v216, v217
	v_cvt_pk_bf16_f32 v13, v252, v253
	v_add_f32_e32 v17, v252, v17
	v_add_f32_e32 v219, v253, v219
	v_fma_f32 v216, v174, s97, -v207
	v_fma_f32 v217, v175, s97, -v207
	v_fma_f32 v252, v176, s97, -v207
	v_fma_f32 v253, v177, s97, -v207
	v_exp_f32_e32 v216, v216
	v_exp_f32_e32 v217, v217
	v_exp_f32_e32 v252, v252
	v_exp_f32_e32 v253, v253
	v_add_f32_e32 v17, v216, v17
	v_add_f32_e32 v219, v217, v219
	v_cvt_pk_bf16_f32 v14, v216, v217
	v_cvt_pk_bf16_f32 v15, v252, v253
	v_add_f32_e32 v17, v252, v17
	v_add_f32_e32 v219, v253, v219
	v_add_f32_e32 v17, v17, v219

; DI void attn_item(const Params& p, char* smem, u16* qbase, const u16* gabase, const u16* kbase, const u16* vtbase,
;                   int tkv, int nkt, int mylimit, const float* lam_p, const int g_wave) {
;     ...
; #pragma unroll
;       for (int d = 0; d < 4; ++d) {
;         const int vrow = 32 * d + r;
; #pragma unroll
;         for (int sp = 0; sp < 4; ++sp) {
;           const u32x2 lo = *(const u32x2*)(Vt + vrow * 128 + ((32 * sp) ^ vz) + 8 * hh);
;           const u32x2 hi = *(const u32x2*)(Vt + vrow * 128 + ((32 * sp + 16) ^ vz) + 8 * hh);
;           u32x4 w = {lo[0], lo[1], hi[0], hi[1]};
;           const bf16x8 vf = *reinterpret_cast<bf16x8*>(&w);
;           O0[d] = __builtin_amdgcn_mfma_f32_32x32x16_bf16(vf, pf0[sp], O0[d], 0, 0, 0);
;           O1[d] = __builtin_amdgcn_mfma_f32_32x32x16_bf16(vf, pf1[sp], O1[d], 0, 0, 0);
;         }
;         __builtin_amdgcn_sched_barrier(0);
;       }
.Lat_nr1:
	s_waitcnt lgkmcnt(1)
	v_mfma_f32_32x32x16_bf16 v[66:81], v[170:173], v[178:181], v[66:81]
	v_fma_f32 v220, v220, s97, -v2
	v_fma_f32 v221, v221, s97, -v2
	v_fma_f32 v222, v222, s97, -v2
	v_fma_f32 v223, v223, s97, -v2
	v_fma_f32 v224, v224, s97, -v2
	v_fma_f32 v225, v225, s97, -v2
	v_fma_f32 v226, v226, s97, -v2
	v_fma_f32 v227, v227, s97, -v2
	s_waitcnt lgkmcnt(0)
	v_mfma_f32_32x32x16_bf16 v[34:49], v[174:177], v[178:181], v[34:49]
	v_exp_f32_e32 v220, v220
	v_exp_f32_e32 v221, v221
	v_exp_f32_e32 v222, v222
	v_exp_f32_e32 v223, v223
	v_exp_f32_e32 v224, v224
	v_exp_f32_e32 v225, v225
	v_exp_f32_e32 v226, v226
	v_exp_f32_e32 v227, v227
	v_add_f32_e32 v17, v222, v220
	v_add_f32_e32 v219, v223, v221
	v_add_f32_e32 v17, v224, v17
	v_add_f32_e32 v219, v225, v219
	v_add_f32_e32 v17, v226, v17
	v_add_f32_e32 v219, v227, v219
	v_cvt_pk_bf16_f32 v220, v220, v221
	v_cvt_pk_bf16_f32 v221, v222, v223
	v_cvt_pk_bf16_f32 v222, v224, v225
	v_cvt_pk_bf16_f32 v223, v226, v227
	s_nop 1
	v_mfma_f32_32x32x16_bf16 v[114:129], v[162:165], v[220:223], v[114:129]
	ds_read_b128 v[162:165], v201 offset:32768
	v_fma_f32 v228, v228, s97, -v2
	v_fma_f32 v229, v229, s97, -v2
	v_fma_f32 v230, v230, s97, -v2
	v_fma_f32 v231, v231, s97, -v2
	v_fma_f32 v232, v232, s97, -v2
	v_fma_f32 v233, v233, s97, -v2
	v_fma_f32 v234, v234, s97, -v2
	v_mfma_f32_32x32x16_bf16 v[82:97], v[166:169], v[220:223], v[82:97]
	ds_read_b128 v[166:169], v201 offset:36864
	v_fma_f32 v235, v235, s97, -v2
	v_exp_f32_e32 v228, v228
	v_exp_f32_e32 v229, v229
	v_exp_f32_e32 v230, v230
	v_exp_f32_e32 v231, v231
	v_exp_f32_e32 v232, v232
	v_exp_f32_e32 v233, v233
	v_mfma_f32_32x32x16_bf16 v[50:65], v[170:173], v[220:223], v[50:65]
	ds_read_b128 v[170:173], v201 offset:40960
	v_exp_f32_e32 v234, v234
	v_exp_f32_e32 v235, v235
	v_add_f32_e32 v17, v228, v17
	v_add_f32_e32 v219, v229, v219
	v_add_f32_e32 v17, v230, v17
	v_add_f32_e32 v219, v231, v219
	v_add_f32_e32 v17, v232, v17
	v_mfma_f32_32x32x16_bf16 v[18:33], v[174:177], v[220:223], v[18:33]
	ds_read_b128 v[174:177], v201 offset:45056
	v_add_f32_e32 v219, v233, v219
	v_add_f32_e32 v17, v234, v17
	v_add_f32_e32 v219, v235, v219
	v_cvt_pk_bf16_f32 v228, v228, v229
	v_cvt_pk_bf16_f32 v229, v230, v231
	v_cvt_pk_bf16_f32 v230, v232, v233
	v_cvt_pk_bf16_f32 v231, v234, v235
	s_waitcnt lgkmcnt(3)
	v_mfma_f32_32x32x16_bf16 v[130:145], v[162:165], v[12:15], v[130:145]
	v_fma_f32 v236, v236, s97, -v2
	v_fma_f32 v237, v237, s97, -v2
	v_fma_f32 v238, v238, s97, -v2
	v_fma_f32 v239, v239, s97, -v2
	v_mfma_f32_32x32x16_bf16 v[114:129], v[162:165], v[228:231], v[114:129]
	ds_read_b128 v[162:165], v202 offset:32768
	v_fma_f32 v240, v240, s97, -v2
	v_fma_f32 v241, v241, s97, -v2
	v_fma_f32 v242, v242, s97, -v2
	v_fma_f32 v243, v243, s97, -v2
	s_waitcnt lgkmcnt(3)
	v_mfma_f32_32x32x16_bf16 v[98:113], v[166:169], v[12:15], v[98:113]
	v_exp_f32_e32 v236, v236
	v_exp_f32_e32 v237, v237
	v_exp_f32_e32 v238, v238
	v_exp_f32_e32 v239, v239
	v_mfma_f32_32x32x16_bf16 v[82:97], v[166:169], v[228:231], v[82:97]
	ds_read_b128 v[166:169], v202 offset:36864
	v_exp_f32_e32 v240, v240
	v_exp_f32_e32 v241, v241
	v_exp_f32_e32 v242, v242
	v_exp_f32_e32 v243, v243
	s_waitcnt lgkmcnt(3)
	v_mfma_f32_32x32x16_bf16 v[66:81], v[170:173], v[12:15], v[66:81]
	v_add_f32_e32 v17, v236, v17
	v_add_f32_e32 v219, v237, v219
	v_add_f32_e32 v17, v238, v17
	v_add_f32_e32 v219, v239, v219
	v_mfma_f32_32x32x16_bf16 v[50:65], v[170:173], v[228:231], v[50:65]
	ds_read_b128 v[170:173], v202 offset:40960
	v_add_f32_e32 v17, v240, v17
	v_add_f32_e32 v219, v241, v219
	v_add_f32_e32 v17, v242, v17
	v_add_f32_e32 v219, v243, v219
	s_waitcnt lgkmcnt(3)
	v_mfma_f32_32x32x16_bf16 v[34:49], v[174:177], v[12:15], v[34:49]
	v_cvt_pk_bf16_f32 v236, v236, v237
	v_cvt_pk_bf16_f32 v237, v238, v239
	v_cvt_pk_bf16_f32 v238, v240, v241
	v_cvt_pk_bf16_f32 v239, v242, v243
	v_mfma_f32_32x32x16_bf16 v[18:33], v[174:177], v[228:231], v[18:33]
	ds_read_b128 v[174:177], v202 offset:45056
	s_waitcnt lgkmcnt(3)
	v_mfma_f32_32x32x16_bf16 v[114:129], v[162:165], v[236:239], v[114:129]
	v_fma_f32 v216, v146, s97, -v207
	v_fma_f32 v217, v147, s97, -v207
	v_fma_f32 v252, v148, s97, -v207
	v_fma_f32 v253, v149, s97, -v207
	v_exp_f32_e32 v216, v216
	v_exp_f32_e32 v217, v217
	v_exp_f32_e32 v252, v252
	v_exp_f32_e32 v253, v253
	v_cvt_pk_bf16_f32 v8, v216, v217
	v_cvt_pk_bf16_f32 v9, v252, v253
	v_add_f32_e32 v254, v252, v216
	v_add_f32_e32 v204, v253, v217
	s_waitcnt lgkmcnt(2)
	v_mfma_f32_32x32x16_bf16 v[82:97], v[166:169], v[236:239], v[82:97]
	v_fma_f32 v216, v150, s97, -v207
	v_fma_f32 v217, v151, s97, -v207
	v_fma_f32 v252, v152, s97, -v207
	v_fma_f32 v253, v153, s97, -v207
	v_exp_f32_e32 v216, v216
	v_exp_f32_e32 v217, v217
	v_exp_f32_e32 v252, v252
	v_exp_f32_e32 v253, v253
	v_add_f32_e32 v254, v216, v254
	v_add_f32_e32 v204, v217, v204
	v_cvt_pk_bf16_f32 v10, v216, v217
	v_cvt_pk_bf16_f32 v11, v252, v253
	v_add_f32_e32 v254, v252, v254
	v_add_f32_e32 v204, v253, v204
	s_waitcnt lgkmcnt(1)
	v_mfma_f32_32x32x16_bf16 v[50:65], v[170:173], v[236:239], v[50:65]
	v_fma_f32 v216, v154, s97, -v207
	v_fma_f32 v217, v155, s97, -v207
	v_fma_f32 v252, v156, s97, -v207
	v_fma_f32 v253, v157, s97, -v207
	v_exp_f32_e32 v216, v216
	v_exp_f32_e32 v217, v217
	v_exp_f32_e32 v252, v252
	v_exp_f32_e32 v253, v253
	v_add_f32_e32 v254, v216, v254
	v_add_f32_e32 v204, v217, v204
	v_cvt_pk_bf16_f32 v4, v216, v217
	v_cvt_pk_bf16_f32 v5, v252, v253
	v_add_f32_e32 v254, v252, v254
	v_add_f32_e32 v204, v253, v204
	s_waitcnt lgkmcnt(0)
	v_mfma_f32_32x32x16_bf16 v[18:33], v[174:177], v[236:239], v[18:33]
	v_fma_f32 v216, v158, s97, -v207
	v_fma_f32 v217, v159, s97, -v207
	v_fma_f32 v252, v160, s97, -v207
	v_fma_f32 v253, v161, s97, -v207
	v_exp_f32_e32 v216, v216
	v_exp_f32_e32 v217, v217
	v_exp_f32_e32 v252, v252
	v_exp_f32_e32 v253, v253
	v_add_f32_e32 v254, v216, v254
	v_add_f32_e32 v204, v217, v204
	v_cvt_pk_bf16_f32 v6, v216, v217
	v_cvt_pk_bf16_f32 v7, v252, v253
	v_add_f32_e32 v254, v252, v254
	v_add_f32_e32 v204, v253, v204
	v_add_f32_e32 v254, v254, v204
	v_cmp_lt_f32_e32 vcc, 0x43800000, v254
	s_cmp_lg_u64 vcc, 0
	s_cbranch_scc0 .Lat_ok0b
	s_nop 15
	s_nop 15
	v_max3_f32 v254, v146, v147, v148
	v_max3_f32 v254, v254, v149, v150
	v_max3_f32 v254, v254, v151, v152
	v_max3_f32 v254, v254, v153, v154
	v_max3_f32 v254, v254, v155, v156
	v_max3_f32 v254, v254, v157, v158
	v_max3_f32 v254, v254, v159, v160
	v_max_f32_e32 v254, v254, v161
	v_mov_b32_e32 v204, v254
	s_nop 1
	v_permlane32_swap_b32_e32 v254, v204
	v_max_f32_e32 v254, v254, v204
	v_mul_f32_e32 v254, s97, v254
	v_max_f32_e32 v204, v207, v254
	v_sub_f32_e32 v216, v207, v204
	v_exp_f32_e32 v216, v216
	v_mov_b32_e32 v207, v204
	s_nop 0
	v_pk_mul_f32 v[144:145], v[144:145], v[216:217] op_sel_hi:[1,0]
	v_pk_mul_f32 v[142:143], v[142:143], v[216:217] op_sel_hi:[1,0]
	v_pk_mul_f32 v[140:141], v[140:141], v[216:217] op_sel_hi:[1,0]
	v_pk_mul_f32 v[138:139], v[138:139], v[216:217] op_sel_hi:[1,0]
	v_pk_mul_f32 v[136:137], v[136:137], v[216:217] op_sel_hi:[1,0]
	v_pk_mul_f32 v[134:135], v[134:135], v[216:217] op_sel_hi:[1,0]
	v_pk_mul_f32 v[132:133], v[132:133], v[216:217] op_sel_hi:[1,0]
	v_pk_mul_f32 v[130:131], v[130:131], v[216:217] op_sel_hi:[1,0]
	v_pk_mul_f32 v[112:113], v[112:113], v[216:217] op_sel_hi:[1,0]
	v_pk_mul_f32 v[110:111], v[110:111], v[216:217] op_sel_hi:[1,0]
	v_pk_mul_f32 v[108:109], v[108:109], v[216:217] op_sel_hi:[1,0]
	v_pk_mul_f32 v[106:107], v[106:107], v[216:217] op_sel_hi:[1,0]
	v_pk_mul_f32 v[104:105], v[104:105], v[216:217] op_sel_hi:[1,0]
	v_pk_mul_f32 v[102:103], v[102:103], v[216:217] op_sel_hi:[1,0]
	v_pk_mul_f32 v[100:101], v[100:101], v[216:217] op_sel_hi:[1,0]
	v_pk_mul_f32 v[98:99], v[98:99], v[216:217] op_sel_hi:[1,0]
	v_pk_mul_f32 v[80:81], v[80:81], v[216:217] op_sel_hi:[1,0]
	v_pk_mul_f32 v[78:79], v[78:79], v[216:217] op_sel_hi:[1,0]
	v_pk_mul_f32 v[76:77], v[76:77], v[216:217] op_sel_hi:[1,0]
	v_pk_mul_f32 v[74:75], v[74:75], v[216:217] op_sel_hi:[1,0]
	v_pk_mul_f32 v[72:73], v[72:73], v[216:217] op_sel_hi:[1,0]
	v_pk_mul_f32 v[70:71], v[70:71], v[216:217] op_sel_hi:[1,0]
	v_pk_mul_f32 v[68:69], v[68:69], v[216:217] op_sel_hi:[1,0]
	v_pk_mul_f32 v[66:67], v[66:67], v[216:217] op_sel_hi:[1,0]
	v_pk_mul_f32 v[48:49], v[48:49], v[216:217] op_sel_hi:[1,0]
	v_pk_mul_f32 v[46:47], v[46:47], v[216:217] op_sel_hi:[1,0]
	v_pk_mul_f32 v[44:45], v[44:45], v[216:217] op_sel_hi:[1,0]
	v_pk_mul_f32 v[42:43], v[42:43], v[216:217] op_sel_hi:[1,0]
	v_pk_mul_f32 v[40:41], v[40:41], v[216:217] op_sel_hi:[1,0]
	v_pk_mul_f32 v[38:39], v[38:39], v[216:217] op_sel_hi:[1,0]
	v_pk_mul_f32 v[36:37], v[36:37], v[216:217] op_sel_hi:[1,0]
	v_pk_mul_f32 v[34:35], v[34:35], v[216:217] op_sel_hi:[1,0]
	v_mul_f32_e32 v186, v186, v216
	v_fma_f32 v216, v146, s97, -v207
	v_fma_f32 v217, v147, s97, -v207
	v_fma_f32 v252, v148, s97, -v207
	v_fma_f32 v253, v149, s97, -v207
	v_exp_f32_e32 v216, v216
	v_exp_f32_e32 v217, v217
	v_exp_f32_e32 v252, v252
	v_exp_f32_e32 v253, v253
	v_cvt_pk_bf16_f32 v8, v216, v217
	v_cvt_pk_bf16_f32 v9, v252, v253
	v_add_f32_e32 v254, v252, v216
	v_add_f32_e32 v204, v253, v217
	v_fma_f32 v216, v150, s97, -v207
	v_fma_f32 v217, v151, s97, -v207
	v_fma_f32 v252, v152, s97, -v207
	v_fma_f32 v253, v153, s97, -v207
	v_exp_f32_e32 v216, v216
	v_exp_f32_e32 v217, v217
	v_exp_f32_e32 v252, v252
	v_exp_f32_e32 v253, v253
	v_add_f32_e32 v254, v216, v254
	v_add_f32_e32 v204, v217, v204
	v_cvt_pk_bf16_f32 v10, v216, v217
	v_cvt_pk_bf16_f32 v11, v252, v253
	v_add_f32_e32 v254, v252, v254
	v_add_f32_e32 v204, v253, v204
	v_fma_f32 v216, v154, s97, -v207
	v_fma_f32 v217, v155, s97, -v207
	v_fma_f32 v252, v156, s97, -v207
	v_fma_f32 v253, v157, s97, -v207
	v_exp_f32_e32 v216, v216
	v_exp_f32_e32 v217, v217
	v_exp_f32_e32 v252, v252
	v_exp_f32_e32 v253, v253
	v_add_f32_e32 v254, v216, v254
	v_add_f32_e32 v204, v217, v204
	v_cvt_pk_bf16_f32 v4, v216, v217
	v_cvt_pk_bf16_f32 v5, v252, v253
	v_add_f32_e32 v254, v252, v254
	v_add_f32_e32 v204, v253, v204
	v_fma_f32 v216, v158, s97, -v207
	v_fma_f32 v217, v159, s97, -v207
	v_fma_f32 v252, v160, s97, -v207
	v_fma_f32 v253, v161, s97, -v207
	v_exp_f32_e32 v216, v216
	v_exp_f32_e32 v217, v217
	v_exp_f32_e32 v252, v252
	v_exp_f32_e32 v253, v253
	v_add_f32_e32 v254, v216, v254
	v_add_f32_e32 v204, v217, v204
	v_cvt_pk_bf16_f32 v6, v216, v217
	v_cvt_pk_bf16_f32 v7, v252, v253
	v_add_f32_e32 v254, v252, v254
	v_add_f32_e32 v204, v253, v204
	v_add_f32_e32 v254, v254, v204
